# rmsnorm (bf16 residual to H) row loop software-pipelined: next four rows' loads issued after the gamma loads into a second register set
# baseline (speedup 1.0000x reference)
; #define OPQV(x) asm volatile("" : "+v"(x))
; DEV void unpack8(const u32x4 v, float (&f)[8]) { f[0] = bflo(v.x); f[1] = bfhi(v.x); f[2] = bflo(v.y); f[3] = bfhi(v.y); f[4] = bflo(v.z); f[5] = bfhi(v.z); f[6] = bflo(v.w); f[7] = bfhi(v.w); }
; template <int RB>
; DEV void rmsnorm_rows(const float* srcf, const bf16_t* srcb, const float* gamma, bf16_t* H, bf16_t* cpy, float* outn, int row0, int lane) {
;     ...
;         u32x4 raw[RB][2];
; #pragma unroll
;         for (int r = 0; r < RB; ++r)
; #pragma unroll
;             for (int hf = 0; hf < 2; ++hf) raw[r][hf] = *(const u32x4*)(srcb + (size_t)(row0 + r) * 1024 + hf * 512 + lane * 8);
; #pragma unroll
;         for (int r = 0; r < RB; ++r)
; #pragma unroll
;             for (int hf = 0; hf < 2; ++hf) { float t8[8]; unpack8(raw[r][hf], t8);
; #pragma unroll
;                 for (int j = 0; j < 8; ++j) v[r][hf * 8 + j] = t8[j]; }
;     }
;     f32x4 g0[2], g1[2];
; #pragma unroll
;     for (int hf = 0; hf < 2; ++hf) { g0[hf] = *(const f32x4*)(gamma + hf * 512 + lane * 8); g1[hf] = *(const f32x4*)(gamma + hf * 512 + lane * 8 + 4); }
; #pragma unroll
;     for (int r = 0; r < RB; ++r) {
;         float ss = 0.f;
; #pragma unroll
;         for (int j = 0; j < 16; ++j) ss += v[r][j] * v[r][j];
;         ss = wave_sum(ss);
; DEV void phase_rmsnorm(const float* srcf, const bf16_t* srcb, const float* gamma, bf16_t* H, bf16_t* cpy, float* outn) {
;     int tid = threadIdx.x; OPQV(tid); const int lane = tid & 63, wave = tid >> 6;
;     for (int rq = blockIdx.x * 8 + wave; rq < T_ / 4; rq += gridDim.x * 8) rmsnorm_rows<4>(srcf, srcb, gamma, H, cpy, outn, rq * 4, lane);
.LBB0_50:
	v_mov_b32_e32 v0, v210
	s_movk_i32 s4, 0x1000
	v_ashrrev_i32_e32 v2, 6, v0
	v_add_u32_e32 v48, s89, v2
	v_cmp_gt_i32_e32 vcc, s4, v48
	s_and_saveexec_b64 s[40:41], vcc
	s_cbranch_execz .LBB0_53
	s_load_dwordx2 s[4:5], s[0:1], 0x80
	s_lshl_b32 s6, s14, 10
	s_ashr_i32 s7, s6, 31
	v_lshlrev_b32_e32 v0, 3, v0
	s_lshl_b64 s[6:7], s[6:7], 2
	s_waitcnt lgkmcnt(0)
	s_add_u32 s4, s4, s6
	v_and_b32_e32 v3, 0x1f8, v0
	s_addc_u32 s5, s5, s7
	v_lshlrev_b32_e32 v0, 1, v3
	v_lshlrev_b32_e32 v4, 2, v3
	v_mov_b32_e32 v5, v1
	v_and_b32_e32 v3, 64, v213
	v_lshl_add_u64 v[34:35], s[4:5], 0, v[4:5]
	v_add_u32_e32 v3, 64, v3
	v_xor_b32_e32 v4, 32, v213
	v_cmp_lt_i32_e32 vcc, v4, v3
	v_readlane_b32 s5, v254, 30
	v_lshl_add_u64 v[32:33], s[18:19], 0, v[0:1]
	v_cndmask_b32_e32 v4, v213, v4, vcc
	v_lshlrev_b32_e32 v49, 2, v4
	v_xor_b32_e32 v4, 16, v213
	v_cmp_lt_i32_e32 vcc, v4, v3
	s_lshl_b32 s4, s71, 3
	v_lshl_add_u64 v[36:37], s[34:35], 0, v[0:1]
	v_cndmask_b32_e32 v4, v213, v4, vcc
	v_lshlrev_b32_e32 v50, 2, v4
	v_xor_b32_e32 v4, 8, v213
	v_cmp_lt_i32_e32 vcc, v4, v3
	v_lshl_add_u32 v38, v2, 2, s5
	s_lshl_b32 s5, s71, 5
	v_cndmask_b32_e32 v4, v213, v4, vcc
	v_lshlrev_b32_e32 v51, 2, v4
	v_xor_b32_e32 v4, 4, v213
	v_cmp_lt_i32_e32 vcc, v4, v3
	s_mov_b64 s[42:43], 0
	s_nop 0
	v_cndmask_b32_e32 v4, v213, v4, vcc
	v_lshlrev_b32_e32 v52, 2, v4
	v_xor_b32_e32 v4, 2, v213
	v_cmp_lt_i32_e32 vcc, v4, v3
	s_nop 1
	v_cndmask_b32_e32 v4, v213, v4, vcc
	v_lshlrev_b32_e32 v53, 2, v4
	v_xor_b32_e32 v4, 1, v213
	v_cmp_lt_i32_e32 vcc, v4, v3
	s_nop 1
	v_cndmask_b32_e32 v3, v213, v4, vcc
	v_lshlrev_b32_e32 v54, 2, v3
	v_ashrrev_i32_e32 v137, 31, v38
	v_mov_b32_e32 v136, v38
	v_lshlrev_b64 v[136:137], 11, v[136:137]
	v_lshl_add_u64 v[136:137], v[32:33], 0, v[136:137]
	v_add_co_u32_e32 v138, vcc, 0x1000, v136
	s_nop 1
	v_addc_co_u32_e32 v139, vcc, 0, v137, vcc
	global_load_dwordx4 v[104:107], v[136:137], off
	global_load_dwordx4 v[108:111], v[136:137], off offset:1024
	global_load_dwordx4 v[112:115], v[136:137], off offset:2048
	global_load_dwordx4 v[116:119], v[136:137], off offset:3072
	global_load_dwordx4 v[120:123], v[138:139], off
	global_load_dwordx4 v[124:127], v[138:139], off offset:1024
	global_load_dwordx4 v[128:131], v[138:139], off offset:2048
	global_load_dwordx4 v[132:135], v[138:139], off offset:3072
	s_waitcnt vmcnt(0)
.LBB0_52:
	v_ashrrev_i32_e32 v39, 31, v38
	v_lshlrev_b64 v[46:47], 11, v[38:39]
	v_lshl_add_u64 v[2:3], v[32:33], 0, v[46:47]
	v_add_u32_e32 v2, 1, v38
	v_ashrrev_i32_e32 v3, 31, v2
	v_lshlrev_b64 v[44:45], 11, v[2:3]
	v_lshl_add_u64 v[2:3], v[32:33], 0, v[44:45]
	v_add_u32_e32 v2, 2, v38
	v_ashrrev_i32_e32 v3, 31, v2
	v_lshlrev_b64 v[42:43], 11, v[2:3]
	v_lshl_add_u64 v[2:3], v[32:33], 0, v[42:43]
	v_add_u32_e32 v2, 3, v38
	v_ashrrev_i32_e32 v3, 31, v2
	v_lshlrev_b64 v[40:41], 11, v[2:3]
	v_lshl_add_u64 v[2:3], v[32:33], 0, v[40:41]
	s_nop 0
	v_lshl_add_u64 v[44:45], v[36:37], 0, v[44:45]
	v_add_u32_e32 v48, s4, v48
	v_add_u32_e32 v38, s5, v38
	v_mov_b64_e32 v[6:7], v[104:105]
	v_mov_b64_e32 v[8:9], v[106:107]
	v_mov_b64_e32 v[28:29], v[108:109]
	v_mov_b64_e32 v[30:31], v[110:111]
	v_mov_b64_e32 v[10:11], v[112:113]
	v_mov_b64_e32 v[12:13], v[114:115]
	v_mov_b64_e32 v[24:25], v[116:117]
	v_mov_b64_e32 v[26:27], v[118:119]
	v_mov_b64_e32 v[14:15], v[120:121]
	v_mov_b64_e32 v[16:17], v[122:123]
	v_mov_b64_e32 v[20:21], v[124:125]
	v_mov_b64_e32 v[22:23], v[126:127]
	v_mov_b64_e32 v[100:101], v[128:129]
	v_mov_b64_e32 v[102:103], v[130:131]
	v_mov_b64_e32 v[2:3], v[132:133]
	v_mov_b64_e32 v[4:5], v[134:135]
	v_lshlrev_b32_e32 v97, 16, v6
	v_and_b32_e32 v95, 0xffff0000, v6
	v_lshlrev_b32_e32 v93, 16, v7
	v_and_b32_e32 v91, 0xffff0000, v7
	v_lshlrev_b32_e32 v98, 16, v8
	v_and_b32_e32 v96, 0xffff0000, v8
	v_lshlrev_b32_e32 v94, 16, v9
	v_and_b32_e32 v92, 0xffff0000, v9
	v_lshlrev_b32_e32 v85, 16, v10
	v_and_b32_e32 v83, 0xffff0000, v10
	v_lshlrev_b32_e32 v81, 16, v11
	v_and_b32_e32 v79, 0xffff0000, v11
	v_lshlrev_b32_e32 v86, 16, v12
	v_and_b32_e32 v84, 0xffff0000, v12
	v_lshlrev_b32_e32 v82, 16, v13
	v_and_b32_e32 v80, 0xffff0000, v13
	v_lshlrev_b32_e32 v73, 16, v14
	v_and_b32_e32 v71, 0xffff0000, v14
	v_lshlrev_b32_e32 v69, 16, v15
	v_and_b32_e32 v67, 0xffff0000, v15
	v_lshlrev_b32_e32 v74, 16, v16
	v_and_b32_e32 v72, 0xffff0000, v16
	v_lshlrev_b32_e32 v70, 16, v17
	v_and_b32_e32 v68, 0xffff0000, v17
	v_lshlrev_b32_e32 v66, 16, v20
	v_and_b32_e32 v65, 0xffff0000, v20
	v_lshlrev_b32_e32 v64, 16, v21
	v_and_b32_e32 v63, 0xffff0000, v21
	global_load_dwordx4 v[14:17], v[34:35], off offset:16
	global_load_dwordx4 v[18:21], v[34:35], off
	global_load_dwordx4 v[6:9], v[34:35], off offset:2064
	global_load_dwordx4 v[10:13], v[34:35], off offset:2048
	v_subrev_u32_e32 v145, s5, v38
	v_cmp_ge_i32_e32 vcc, s58, v48
	s_nop 1
	v_cndmask_b32_e32 v144, v145, v38, vcc
	v_ashrrev_i32_e32 v137, 31, v144
	v_mov_b32_e32 v136, v144
	v_lshlrev_b64 v[136:137], 11, v[136:137]
	v_lshl_add_u64 v[136:137], v[32:33], 0, v[136:137]
	v_add_co_u32_e32 v138, vcc, 0x1000, v136
	s_nop 1
	v_addc_co_u32_e32 v139, vcc, 0, v137, vcc
	global_load_dwordx4 v[104:107], v[136:137], off
	global_load_dwordx4 v[108:111], v[136:137], off offset:1024
	global_load_dwordx4 v[112:115], v[136:137], off offset:2048
	global_load_dwordx4 v[116:119], v[136:137], off offset:3072
	global_load_dwordx4 v[120:123], v[138:139], off
	global_load_dwordx4 v[124:127], v[138:139], off offset:1024
	global_load_dwordx4 v[128:131], v[138:139], off offset:2048
	global_load_dwordx4 v[132:135], v[138:139], off offset:3072
	v_mul_f32_e32 v99, v97, v97
	v_fmac_f32_e32 v99, v95, v95
	v_fmac_f32_e32 v99, v93, v93
	v_fmac_f32_e32 v99, v91, v91
	v_fmac_f32_e32 v99, v98, v98
	v_fmac_f32_e32 v99, v96, v96
	v_fmac_f32_e32 v99, v94, v94
	v_lshlrev_b32_e32 v90, 16, v28
	v_fmac_f32_e32 v99, v92, v92
	v_and_b32_e32 v89, 0xffff0000, v28
	v_fmac_f32_e32 v99, v90, v90
	v_lshlrev_b32_e32 v88, 16, v29
	v_fmac_f32_e32 v99, v89, v89
	v_and_b32_e32 v87, 0xffff0000, v29
	s_waitcnt vmcnt(12)
; DEV u32x4 pack8(const float (&f)[8]) { u32x4 w; w.x = cvt_pk_bf16(f[0], f[1]); w.y = cvt_pk_bf16(f[2], f[3]); w.z = cvt_pk_bf16(f[4], f[5]); w.w = cvt_pk_bf16(f[6], f[7]); return w; }
; template <int RB>
; DEV void rmsnorm_rows(const float* srcf, const bf16_t* srcb, const float* gamma, bf16_t* H, bf16_t* cpy, float* outn, int row0, int lane) {
;     ...
;     for (int r = 0; r < RB; ++r) {
;         float ss = 0.f;
; #pragma unroll
;         for (int j = 0; j < 16; ++j) ss += v[r][j] * v[r][j];
;         ss = wave_sum(ss);
;         const float rs = rsqrtf(ss * (1.f / 1024.f) + EPS_);
;         const int row = row0 + r;
; #pragma unroll
;         for (int hf = 0; hf < 2; ++hf) { const int c = hf * 512 + lane * 8;
;             float y[8], x8[8];
; #pragma unroll
;             for (int j = 0; j < 4; ++j) { y[j] = v[r][hf * 8 + j] * rs * g0[hf][j]; y[4 + j] = v[r][hf * 8 + 4 + j] * rs * g1[hf][j]; }
; #pragma unroll
;             for (int j = 0; j < 8; ++j) x8[j] = v[r][hf * 8 + j];
;             if (cpy) *(u32x4*)(cpy + (size_t)row * 1024 + c) = pack8(x8);
;             if (outn) { *(f32x4*)(outn + (size_t)row * 1024 + c) = (f32x4){y[0], y[1], y[2], y[3]}; *(f32x4*)(outn + (size_t)row * 1024 + c + 4) = (f32x4){y[4], y[5], y[6], y[7]}; }
;             if (H) *(u32x4*)(H + (size_t)row * 1024 + c) = pack8(y); }
	v_lshlrev_b32_e32 v39, 16, v2
	v_and_b32_e32 v29, 0xffff0000, v2
	v_lshlrev_b32_e32 v28, 16, v3
	v_and_b32_e32 v0, 0xffff0000, v3
	v_fmac_f32_e32 v99, v88, v88
	v_and_b32_e32 v2, 0xffff0000, v30
	v_lshlrev_b32_e32 v3, 16, v30
	v_lshlrev_b32_e32 v78, 16, v24
	v_and_b32_e32 v77, 0xffff0000, v24
	v_lshlrev_b32_e32 v76, 16, v25
	v_and_b32_e32 v75, 0xffff0000, v25
	v_fmac_f32_e32 v99, v87, v87
	v_pk_mul_f32 v[24:25], v[2:3], v[2:3]
	v_lshlrev_b32_e32 v61, 16, v100
	v_add_f32_e32 v25, v25, v99
	v_add_f32_e32 v99, v24, v25
	v_and_b32_e32 v24, 0xffff0000, v31
	v_lshlrev_b32_e32 v25, 16, v31
	v_pk_mul_f32 v[30:31], v[24:25], v[24:25]
	v_and_b32_e32 v59, 0xffff0000, v100
	v_add_f32_e32 v31, v31, v99
	v_add_f32_e32 v30, v30, v31
	ds_bpermute_b32 v31, v49, v30
	v_lshlrev_b32_e32 v57, 16, v101
	v_and_b32_e32 v55, 0xffff0000, v101
	v_lshlrev_b32_e32 v62, 16, v102
	v_and_b32_e32 v60, 0xffff0000, v102
	s_waitcnt lgkmcnt(0)
	v_add_f32_e32 v30, v30, v31
	ds_bpermute_b32 v31, v50, v30
	v_lshlrev_b32_e32 v58, 16, v103
	v_and_b32_e32 v56, 0xffff0000, v103
	s_waitcnt lgkmcnt(0)
	v_add_f32_e32 v30, v30, v31
	ds_bpermute_b32 v31, v51, v30
	s_waitcnt lgkmcnt(0)
	v_add_f32_e32 v30, v30, v31
	ds_bpermute_b32 v31, v52, v30
	s_waitcnt lgkmcnt(0)
	v_add_f32_e32 v30, v30, v31
	ds_bpermute_b32 v31, v53, v30
	s_waitcnt lgkmcnt(0)
	v_add_f32_e32 v30, v30, v31
	ds_bpermute_b32 v31, v54, v30
	s_waitcnt lgkmcnt(0)
	v_add_f32_e32 v30, v30, v31
	v_fmamk_f32 v30, v30, 0x3a800000, v211
	v_cmp_gt_f32_e32 vcc, s33, v30
	v_mul_f32_e32 v31, 0x4b800000, v30
	s_nop 0
	v_cndmask_b32_e32 v30, v30, v31, vcc
	v_rsq_f32_e32 v30, v30
	s_nop 0
	v_mul_f32_e32 v31, 0x45800000, v30
	v_cndmask_b32_e32 v99, v30, v31, vcc
	v_mul_f32_e32 v30, v99, v97
	v_mul_f32_e32 v31, v99, v98
	v_mul_f32_e32 v93, v99, v93
	s_waitcnt vmcnt(10)
	v_mul_f32_e32 v30, v18, v30
	v_mul_f32_e32 v31, v14, v31
	v_mul_f32_e32 v95, v99, v95
	v_mul_f32_e32 v96, v99, v96
	v_mul_f32_e32 v93, v20, v93
	v_mul_f32_e32 v94, v99, v94
	v_mul_f32_e32 v91, v99, v91
	v_mul_f32_e32 v92, v99, v92
	v_mul_f32_e32 v88, v99, v88
	v_mul_f32_e32 v95, v19, v95
	v_mul_f32_e32 v96, v15, v96
	v_mul_f32_e32 v97, v16, v94
	v_mul_f32_e32 v91, v21, v91
	v_mul_f32_e32 v98, v17, v92
	v_cvt_pk_bf16_f32 v92, v30, v95
	v_cvt_pk_bf16_f32 v93, v93, v91
	v_cvt_pk_bf16_f32 v94, v31, v96
	v_lshl_add_u64 v[30:31], v[36:37], 0, v[46:47]
	v_mul_f32_e32 v46, v99, v90
	v_mul_f32_e32 v3, v99, v3
	v_mul_f32_e32 v47, v99, v89
	v_mul_f32_e32 v2, v99, v2
	s_waitcnt vmcnt(8)
	v_mul_f32_e32 v89, v12, v88
	v_mul_f32_e32 v25, v99, v25
	v_mul_f32_e32 v87, v99, v87
	v_mul_f32_e32 v24, v99, v24
	v_cvt_pk_bf16_f32 v95, v97, v98
	global_store_dwordx4 v[30:31], v[92:95], off
	v_mul_f32_e32 v46, v10, v46
	v_mul_f32_e32 v3, v6, v3
	v_mul_f32_e32 v47, v11, v47
	v_mul_f32_e32 v2, v7, v2
	v_mul_f32_e32 v25, v8, v25
	v_mul_f32_e32 v87, v13, v87
	v_mul_f32_e32 v24, v9, v24
	v_cvt_pk_bf16_f32 v88, v46, v47
	v_cvt_pk_bf16_f32 v89, v89, v87
	v_cvt_pk_bf16_f32 v90, v3, v2
	v_cvt_pk_bf16_f32 v91, v25, v24
	global_store_dwordx4 v[30:31], v[88:91], off offset:1024
	v_mul_f32_e32 v30, v85, v85
	v_fmac_f32_e32 v30, v83, v83
	v_fmac_f32_e32 v30, v81, v81
	v_fmac_f32_e32 v30, v79, v79
	v_fmac_f32_e32 v30, v86, v86
	v_fmac_f32_e32 v30, v84, v84
	v_fmac_f32_e32 v30, v82, v82
	v_fmac_f32_e32 v30, v80, v80
	v_fmac_f32_e32 v30, v78, v78
	v_fmac_f32_e32 v30, v77, v77
	v_fmac_f32_e32 v30, v76, v76
	v_and_b32_e32 v2, 0xffff0000, v26
	v_lshlrev_b32_e32 v3, 16, v26
	v_fmac_f32_e32 v30, v75, v75
	v_pk_mul_f32 v[24:25], v[2:3], v[2:3]
	v_lshlrev_b32_e32 v31, 16, v27
	v_add_f32_e32 v25, v25, v30
	v_and_b32_e32 v30, 0xffff0000, v27
	v_add_f32_e32 v26, v24, v25
	v_pk_mul_f32 v[24:25], v[30:31], v[30:31]
	s_nop 0
	v_add_f32_e32 v25, v25, v26
	v_add_f32_e32 v24, v24, v25
	ds_bpermute_b32 v25, v49, v24
	s_waitcnt lgkmcnt(0)
	v_add_f32_e32 v24, v24, v25
	ds_bpermute_b32 v25, v50, v24
	s_waitcnt lgkmcnt(0)
	v_add_f32_e32 v24, v24, v25
	ds_bpermute_b32 v25, v51, v24
	s_waitcnt lgkmcnt(0)
	v_add_f32_e32 v24, v24, v25
	ds_bpermute_b32 v25, v52, v24
	s_waitcnt lgkmcnt(0)
	v_add_f32_e32 v24, v24, v25
	ds_bpermute_b32 v25, v53, v24
	s_waitcnt lgkmcnt(0)
	v_add_f32_e32 v24, v24, v25
	ds_bpermute_b32 v25, v54, v24
	s_waitcnt lgkmcnt(0)
	v_add_f32_e32 v24, v24, v25
	v_fmamk_f32 v24, v24, 0x3a800000, v211
	v_cmp_gt_f32_e32 vcc, s33, v24
	v_mul_f32_e32 v25, 0x4b800000, v24
	s_nop 0
	v_cndmask_b32_e32 v24, v24, v25, vcc
	v_rsq_f32_e32 v24, v24
	s_nop 0
	v_mul_f32_e32 v25, 0x45800000, v24
	v_cndmask_b32_e32 v46, v24, v25, vcc
	v_mul_f32_e32 v25, v46, v86
	v_mul_f32_e32 v24, v46, v85
	v_mul_f32_e32 v26, v14, v25
	v_mul_f32_e32 v25, v46, v83
	v_mul_f32_e32 v24, v18, v24
	v_mul_f32_e32 v25, v19, v25
	v_mul_f32_e32 v27, v46, v84
	v_mul_f32_e32 v47, v46, v81
	v_mul_f32_e32 v79, v46, v79
	v_mul_f32_e32 v27, v15, v27
	v_mul_f32_e32 v47, v20, v47
	v_mul_f32_e32 v81, v46, v82
	v_mul_f32_e32 v79, v21, v79
	v_mul_f32_e32 v80, v46, v80
	v_cvt_pk_bf16_f32 v24, v24, v25
	v_cvt_pk_bf16_f32 v25, v47, v79
	v_cvt_pk_bf16_f32 v26, v26, v27
	v_mul_f32_e32 v81, v16, v81
	v_mul_f32_e32 v80, v17, v80
	v_cvt_pk_bf16_f32 v27, v81, v80
	global_store_dwordx4 v[44:45], v[24:27], off
	v_mul_f32_e32 v3, v46, v3
	v_mul_f32_e32 v2, v46, v2
	v_mul_f32_e32 v24, v46, v78
	v_mul_f32_e32 v25, v46, v77
	v_mul_f32_e32 v26, v46, v76
	v_mul_f32_e32 v24, v10, v24
	v_mul_f32_e32 v25, v11, v25
	v_mul_f32_e32 v26, v12, v26
	v_mul_f32_e32 v27, v46, v31
	v_mul_f32_e32 v31, v46, v75
	v_mul_f32_e32 v3, v6, v3
	v_mul_f32_e32 v2, v7, v2
	v_mul_f32_e32 v27, v8, v27
	v_mul_f32_e32 v31, v13, v31
	v_mul_f32_e32 v30, v46, v30
	v_cvt_pk_bf16_f32 v24, v24, v25
	v_cvt_pk_bf16_f32 v25, v26, v31
	v_cvt_pk_bf16_f32 v26, v3, v2
	v_mul_f32_e32 v30, v9, v30
	v_cvt_pk_bf16_f32 v27, v27, v30
	global_store_dwordx4 v[44:45], v[24:27], off offset:1024
	v_and_b32_e32 v2, 0xffff0000, v22
	v_lshlrev_b32_e32 v3, 16, v22
	v_mul_f32_e32 v26, v73, v73
	v_fmac_f32_e32 v26, v71, v71
	v_fmac_f32_e32 v26, v69, v69
	v_fmac_f32_e32 v26, v67, v67
	v_fmac_f32_e32 v26, v74, v74
	v_fmac_f32_e32 v26, v72, v72
	v_fmac_f32_e32 v26, v70, v70
	v_fmac_f32_e32 v26, v68, v68
	v_fmac_f32_e32 v26, v66, v66
	v_fmac_f32_e32 v26, v65, v65
	v_fmac_f32_e32 v26, v64, v64
	v_fmac_f32_e32 v26, v63, v63
	v_pk_mul_f32 v[24:25], v[2:3], v[2:3]
	v_lshlrev_b32_e32 v27, 16, v23
	v_add_f32_e32 v22, v25, v26
	v_and_b32_e32 v26, 0xffff0000, v23
	v_add_f32_e32 v24, v24, v22
	v_pk_mul_f32 v[22:23], v[26:27], v[26:27]
	s_nop 0
	v_add_f32_e32 v23, v23, v24
	v_add_f32_e32 v22, v22, v23
	ds_bpermute_b32 v23, v49, v22
	s_waitcnt lgkmcnt(0)
; #define OPQV(x) asm volatile("" : "+v"(x))
; DEV u32x4 pack8(const float (&f)[8]) { u32x4 w; w.x = cvt_pk_bf16(f[0], f[1]); w.y = cvt_pk_bf16(f[2], f[3]); w.z = cvt_pk_bf16(f[4], f[5]); w.w = cvt_pk_bf16(f[6], f[7]); return w; }
; template <int RB>
; DEV void rmsnorm_rows(const float* srcf, const bf16_t* srcb, const float* gamma, bf16_t* H, bf16_t* cpy, float* outn, int row0, int lane) {
;     ...
;     for (int r = 0; r < RB; ++r) {
;         float ss = 0.f;
; #pragma unroll
;         for (int j = 0; j < 16; ++j) ss += v[r][j] * v[r][j];
;         ss = wave_sum(ss);
;         const float rs = rsqrtf(ss * (1.f / 1024.f) + EPS_);
;         const int row = row0 + r;
; #pragma unroll
;         for (int hf = 0; hf < 2; ++hf) { const int c = hf * 512 + lane * 8;
;             float y[8], x8[8];
; #pragma unroll
;             for (int j = 0; j < 4; ++j) { y[j] = v[r][hf * 8 + j] * rs * g0[hf][j]; y[4 + j] = v[r][hf * 8 + 4 + j] * rs * g1[hf][j]; }
; #pragma unroll
;             for (int j = 0; j < 8; ++j) x8[j] = v[r][hf * 8 + j];
;             if (cpy) *(u32x4*)(cpy + (size_t)row * 1024 + c) = pack8(x8);
;             if (outn) { *(f32x4*)(outn + (size_t)row * 1024 + c) = (f32x4){y[0], y[1], y[2], y[3]}; *(f32x4*)(outn + (size_t)row * 1024 + c + 4) = (f32x4){y[4], y[5], y[6], y[7]}; }
;             if (H) *(u32x4*)(H + (size_t)row * 1024 + c) = pack8(y); }
;     }
; }
; DEV void phase_rmsnorm(const float* srcf, const bf16_t* srcb, const float* gamma, bf16_t* H, bf16_t* cpy, float* outn) {
;     int tid = threadIdx.x; OPQV(tid); const int lane = tid & 63, wave = tid >> 6;
;     for (int rq = blockIdx.x * 8 + wave; rq < T_ / 4; rq += gridDim.x * 8) rmsnorm_rows<4>(srcf, srcb, gamma, H, cpy, outn, rq * 4, lane);
	v_add_f32_e32 v22, v22, v23
	ds_bpermute_b32 v23, v50, v22
	s_waitcnt lgkmcnt(0)
	v_add_f32_e32 v22, v22, v23
	ds_bpermute_b32 v23, v51, v22
	s_waitcnt lgkmcnt(0)
	v_add_f32_e32 v22, v22, v23
	ds_bpermute_b32 v23, v52, v22
	s_waitcnt lgkmcnt(0)
	v_add_f32_e32 v22, v22, v23
	ds_bpermute_b32 v23, v53, v22
	s_waitcnt lgkmcnt(0)
	v_add_f32_e32 v22, v22, v23
	ds_bpermute_b32 v23, v54, v22
	s_waitcnt lgkmcnt(0)
	v_add_f32_e32 v22, v22, v23
	v_fmamk_f32 v22, v22, 0x3a800000, v211
	v_cmp_gt_f32_e32 vcc, s33, v22
	v_mul_f32_e32 v23, 0x4b800000, v22
	s_nop 0
	v_cndmask_b32_e32 v22, v22, v23, vcc
	v_rsq_f32_e32 v22, v22
	s_nop 0
	v_mul_f32_e32 v23, 0x45800000, v22
	v_cndmask_b32_e32 v44, v22, v23, vcc
	v_mul_f32_e32 v23, v44, v74
	v_mul_f32_e32 v22, v44, v73
	v_mul_f32_e32 v24, v14, v23
	v_mul_f32_e32 v23, v44, v71
	v_mul_f32_e32 v25, v44, v72
	v_mul_f32_e32 v30, v44, v69
	v_mul_f32_e32 v31, v44, v70
	v_mul_f32_e32 v22, v18, v22
	v_mul_f32_e32 v23, v19, v23
	v_mul_f32_e32 v25, v15, v25
	v_mul_f32_e32 v30, v20, v30
	v_mul_f32_e32 v31, v16, v31
	v_mul_f32_e32 v45, v44, v67
	v_mul_f32_e32 v46, v44, v68
	v_mul_f32_e32 v45, v21, v45
	v_mul_f32_e32 v46, v17, v46
	v_cvt_pk_bf16_f32 v22, v22, v23
	v_cvt_pk_bf16_f32 v23, v30, v45
	v_cvt_pk_bf16_f32 v24, v24, v25
	v_cvt_pk_bf16_f32 v25, v31, v46
	v_lshl_add_u64 v[30:31], v[36:37], 0, v[42:43]
	global_store_dwordx4 v[30:31], v[22:25], off
	v_mul_f32_e32 v3, v44, v3
	v_mul_f32_e32 v2, v44, v2
	v_mul_f32_e32 v22, v44, v66
	v_mul_f32_e32 v23, v44, v65
	v_mul_f32_e32 v24, v44, v64
	v_mul_f32_e32 v22, v10, v22
	v_mul_f32_e32 v23, v11, v23
	v_mul_f32_e32 v24, v12, v24
	v_mul_f32_e32 v25, v44, v27
	v_mul_f32_e32 v27, v44, v63
	v_mul_f32_e32 v3, v6, v3
	v_mul_f32_e32 v2, v7, v2
	v_mul_f32_e32 v25, v8, v25
	v_mul_f32_e32 v27, v13, v27
	v_mul_f32_e32 v26, v44, v26
	v_cvt_pk_bf16_f32 v22, v22, v23
	v_cvt_pk_bf16_f32 v23, v24, v27
	v_cvt_pk_bf16_f32 v24, v3, v2
	v_mul_f32_e32 v26, v9, v26
	v_cvt_pk_bf16_f32 v25, v25, v26
	global_store_dwordx4 v[30:31], v[22:25], off offset:1024
	s_nop 1
	v_mul_f32_e32 v24, v61, v61
	v_fmac_f32_e32 v24, v59, v59
	v_fmac_f32_e32 v24, v57, v57
	v_fmac_f32_e32 v24, v55, v55
	v_fmac_f32_e32 v24, v62, v62
	v_fmac_f32_e32 v24, v60, v60
	v_fmac_f32_e32 v24, v58, v58
	v_fmac_f32_e32 v24, v56, v56
	v_fmac_f32_e32 v24, v39, v39
	v_fmac_f32_e32 v24, v29, v29
	v_fmac_f32_e32 v24, v28, v28
	v_and_b32_e32 v22, 0xffff0000, v4
	v_lshlrev_b32_e32 v23, 16, v4
	v_fmac_f32_e32 v24, v0, v0
	v_pk_mul_f32 v[2:3], v[22:23], v[22:23]
	v_lshlrev_b32_e32 v25, 16, v5
	v_add_f32_e32 v3, v3, v24
	v_and_b32_e32 v24, 0xffff0000, v5
	v_add_f32_e32 v4, v2, v3
	v_pk_mul_f32 v[2:3], v[24:25], v[24:25]
	s_nop 0
	v_add_f32_e32 v3, v3, v4
	v_add_f32_e32 v2, v2, v3
	ds_bpermute_b32 v3, v49, v2
	s_waitcnt lgkmcnt(0)
	v_add_f32_e32 v2, v2, v3
	ds_bpermute_b32 v3, v50, v2
	s_waitcnt lgkmcnt(0)
	v_add_f32_e32 v2, v2, v3
	ds_bpermute_b32 v3, v51, v2
	s_waitcnt lgkmcnt(0)
	v_add_f32_e32 v2, v2, v3
	ds_bpermute_b32 v3, v52, v2
	s_waitcnt lgkmcnt(0)
	v_add_f32_e32 v2, v2, v3
	ds_bpermute_b32 v3, v53, v2
	s_waitcnt lgkmcnt(0)
	v_add_f32_e32 v2, v2, v3
	ds_bpermute_b32 v3, v54, v2
	s_waitcnt lgkmcnt(0)
	v_add_f32_e32 v2, v2, v3
	v_fmamk_f32 v2, v2, 0x3a800000, v211
	v_cmp_gt_f32_e32 vcc, s33, v2
	v_mul_f32_e32 v3, 0x4b800000, v2
	s_nop 0
	v_cndmask_b32_e32 v2, v2, v3, vcc
	v_rsq_f32_e32 v2, v2
	s_nop 0
	v_mul_f32_e32 v3, 0x45800000, v2
	v_cndmask_b32_e32 v26, v2, v3, vcc
	v_mul_f32_e32 v3, v26, v62
	v_mul_f32_e32 v5, v26, v60
	v_mul_f32_e32 v2, v26, v61
	v_mul_f32_e32 v4, v14, v3
	v_mul_f32_e32 v3, v26, v59
	v_mul_f32_e32 v5, v15, v5
	v_mul_f32_e32 v14, v26, v57
	v_mul_f32_e32 v15, v26, v58
	v_mul_f32_e32 v2, v18, v2
	v_mul_f32_e32 v3, v19, v3
	v_mul_f32_e32 v14, v20, v14
	v_mul_f32_e32 v15, v16, v15
	v_mul_f32_e32 v16, v26, v55
	v_mul_f32_e32 v18, v26, v56
	v_mul_f32_e32 v16, v21, v16
	v_mul_f32_e32 v17, v17, v18
	v_cvt_pk_bf16_f32 v2, v2, v3
	v_cvt_pk_bf16_f32 v3, v14, v16
	v_cvt_pk_bf16_f32 v4, v4, v5
	v_cvt_pk_bf16_f32 v5, v15, v17
	v_lshl_add_u64 v[14:15], v[36:37], 0, v[40:41]
	global_store_dwordx4 v[14:15], v[2:5], off
	v_cmp_lt_i32_e32 vcc, s58, v48
	v_mul_f32_e32 v0, v26, v0
	v_mul_f32_e32 v3, v26, v23
	v_mul_f32_e32 v5, v26, v22
	v_mul_f32_e32 v2, v26, v39
	v_mul_f32_e32 v4, v6, v3
	v_mul_f32_e32 v3, v26, v29
	v_mul_f32_e32 v5, v7, v5
	v_mul_f32_e32 v7, v26, v25
	v_mul_f32_e32 v2, v10, v2
	v_mul_f32_e32 v3, v11, v3
	v_mul_f32_e32 v6, v26, v28
	v_mul_f32_e32 v7, v8, v7
	v_mul_f32_e32 v8, v26, v24
	s_or_b64 s[42:43], vcc, s[42:43]
	v_mul_f32_e32 v6, v12, v6
	v_mul_f32_e32 v0, v13, v0
	v_mul_f32_e32 v8, v9, v8
	v_cvt_pk_bf16_f32 v2, v2, v3
	v_cvt_pk_bf16_f32 v3, v6, v0
	v_cvt_pk_bf16_f32 v4, v4, v5
	v_cvt_pk_bf16_f32 v5, v7, v8
	global_store_dwordx4 v[14:15], v[2:5], off offset:1024
	s_waitcnt vmcnt(8)
	s_andn2_b64 exec, exec, s[42:43]
	s_cbranch_execnz .LBB0_52
